# FFN-down residual epilogue rewritten as a double-buffered software pipeline with counted vmcnt waits (on top of half-tile round)
# baseline (speedup 1.0000x reference)
.LBB0_1239:
	v_lshlrev_b64 v[152:153], 2, v[152:153]
	v_lshl_add_u64 v[158:159], s[10:11], 0, v[158:159]
	v_lshl_add_u64 v[154:155], v[156:157], 0, v[152:153]
	v_lshl_add_u64 v[152:153], v[158:159], 0, v[152:153]
	s_mov_b32 s40, s37
	s_mov_b32 s39, s38
	global_load_dwordx4 v[156:159], v[154:155], off
	global_load_dwordx4 v[176:179], v[154:155], off offset:16
	global_load_dwordx4 v[180:183], v[154:155], off offset:128
	global_load_dwordx4 v[184:187], v[154:155], off offset:144
	s_mov_b64 s[14:15], 0x10000
	v_lshl_add_u64 v[172:173], v[154:155], 0, s[14:15]
	global_load_dwordx4 v[188:191], v[172:173], off
	global_load_dwordx4 v[192:195], v[172:173], off offset:16
	global_load_dwordx4 v[196:199], v[172:173], off offset:128
	global_load_dwordx4 v[230:233], v[172:173], off offset:144
	s_waitcnt vmcnt(4)
	v_pk_fma_f32 v[142:143], v[142:143], v[110:111], v[156:157]
	v_pk_fma_f32 v[144:145], v[144:145], v[112:113], v[158:159]
	v_pk_fma_f32 v[138:139], v[138:139], v[102:103], v[176:177]
	v_pk_fma_f32 v[140:141], v[140:141], v[104:105], v[178:179]
	v_pk_fma_f32 v[130:131], v[130:131], v[106:107], v[180:181]
	v_pk_fma_f32 v[132:133], v[132:133], v[108:109], v[182:183]
	v_pk_fma_f32 v[126:127], v[126:127], v[98:99], v[184:185]
	v_pk_fma_f32 v[128:129], v[128:129], v[100:101], v[186:187]
	global_store_dwordx4 v[152:153], v[142:145], off
	global_store_dwordx4 v[152:153], v[138:141], off offset:16
	global_store_dwordx4 v[152:153], v[130:133], off offset:128
	global_store_dwordx4 v[152:153], v[126:129], off offset:144
	s_mov_b64 s[14:15], 0x20000
	v_lshl_add_u64 v[172:173], v[154:155], 0, s[14:15]
	global_load_dwordx4 v[156:159], v[172:173], off
	global_load_dwordx4 v[176:179], v[172:173], off offset:16
	global_load_dwordx4 v[180:183], v[172:173], off offset:128
	global_load_dwordx4 v[184:187], v[172:173], off offset:144
	s_waitcnt vmcnt(8)
	v_pk_fma_f32 v[134:135], v[134:135], v[110:111], v[188:189]
	v_pk_fma_f32 v[136:137], v[136:137], v[112:113], v[190:191]
	v_pk_fma_f32 v[122:123], v[122:123], v[102:103], v[192:193]
	v_pk_fma_f32 v[124:125], v[124:125], v[104:105], v[194:195]
	v_pk_fma_f32 v[118:119], v[118:119], v[106:107], v[196:197]
	v_pk_fma_f32 v[120:121], v[120:121], v[108:109], v[198:199]
	v_pk_fma_f32 v[114:115], v[114:115], v[98:99], v[230:231]
	v_pk_fma_f32 v[116:117], v[116:117], v[100:101], v[232:233]
	s_mov_b64 s[14:15], 0x10000
	v_lshl_add_u64 v[174:175], v[152:153], 0, s[14:15]
	global_store_dwordx4 v[174:175], v[134:137], off
	global_store_dwordx4 v[174:175], v[122:125], off offset:16
	global_store_dwordx4 v[174:175], v[118:121], off offset:128
	global_store_dwordx4 v[174:175], v[114:117], off offset:144
	s_mov_b64 s[14:15], 0x30000
	v_lshl_add_u64 v[172:173], v[154:155], 0, s[14:15]
	global_load_dwordx4 v[188:191], v[172:173], off
	global_load_dwordx4 v[192:195], v[172:173], off offset:16
	global_load_dwordx4 v[196:199], v[172:173], off offset:128
	global_load_dwordx4 v[230:233], v[172:173], off offset:144
	s_waitcnt vmcnt(8)
	v_pk_fma_f32 v[94:95], v[94:95], v[110:111], v[156:157]
	v_pk_fma_f32 v[96:97], v[96:97], v[112:113], v[158:159]
	v_pk_fma_f32 v[90:91], v[90:91], v[102:103], v[176:177]
	v_pk_fma_f32 v[92:93], v[92:93], v[104:105], v[178:179]
	v_pk_fma_f32 v[82:83], v[82:83], v[106:107], v[180:181]
	v_pk_fma_f32 v[84:85], v[84:85], v[108:109], v[182:183]
	v_pk_fma_f32 v[78:79], v[78:79], v[98:99], v[184:185]
	v_pk_fma_f32 v[80:81], v[80:81], v[100:101], v[186:187]
	s_mov_b64 s[14:15], 0x20000
	v_lshl_add_u64 v[174:175], v[152:153], 0, s[14:15]
	global_store_dwordx4 v[174:175], v[94:97], off
	global_store_dwordx4 v[174:175], v[90:93], off offset:16
	global_store_dwordx4 v[174:175], v[82:85], off offset:128
	global_store_dwordx4 v[174:175], v[78:81], off offset:144
	s_cmp_lg_u32 s99, 0
	s_cbranch_scc1 .Lfd_epi_h3
	s_mov_b64 s[14:15], 0x80000
	v_lshl_add_u64 v[172:173], v[154:155], 0, s[14:15]
	global_load_dwordx4 v[156:159], v[172:173], off
	global_load_dwordx4 v[176:179], v[172:173], off offset:16
	global_load_dwordx4 v[180:183], v[172:173], off offset:128
	global_load_dwordx4 v[184:187], v[172:173], off offset:144
	s_waitcnt vmcnt(8)
	v_pk_fma_f32 v[86:87], v[86:87], v[110:111], v[188:189]
	v_pk_fma_f32 v[88:89], v[88:89], v[112:113], v[190:191]
	v_pk_fma_f32 v[74:75], v[74:75], v[102:103], v[192:193]
	v_pk_fma_f32 v[76:77], v[76:77], v[104:105], v[194:195]
	v_pk_fma_f32 v[70:71], v[70:71], v[106:107], v[196:197]
	v_pk_fma_f32 v[72:73], v[72:73], v[108:109], v[198:199]
	v_pk_fma_f32 v[66:67], v[66:67], v[98:99], v[230:231]
	v_pk_fma_f32 v[68:69], v[68:69], v[100:101], v[232:233]
	s_mov_b64 s[14:15], 0x30000
	v_lshl_add_u64 v[174:175], v[152:153], 0, s[14:15]
	global_store_dwordx4 v[174:175], v[86:89], off
	global_store_dwordx4 v[174:175], v[74:77], off offset:16
	global_store_dwordx4 v[174:175], v[70:73], off offset:128
	global_store_dwordx4 v[174:175], v[66:69], off offset:144
	s_mov_b64 s[14:15], 0x90000
	v_lshl_add_u64 v[172:173], v[154:155], 0, s[14:15]
	global_load_dwordx4 v[188:191], v[172:173], off
	global_load_dwordx4 v[192:195], v[172:173], off offset:16
	global_load_dwordx4 v[196:199], v[172:173], off offset:128
	global_load_dwordx4 v[230:233], v[172:173], off offset:144
	s_waitcnt vmcnt(8)
	v_pk_fma_f32 v[62:63], v[62:63], v[110:111], v[156:157]
	v_pk_fma_f32 v[64:65], v[64:65], v[112:113], v[158:159]
	v_pk_fma_f32 v[58:59], v[58:59], v[102:103], v[176:177]
	v_pk_fma_f32 v[60:61], v[60:61], v[104:105], v[178:179]
	v_pk_fma_f32 v[50:51], v[50:51], v[106:107], v[180:181]
	v_pk_fma_f32 v[52:53], v[52:53], v[108:109], v[182:183]
	v_pk_fma_f32 v[46:47], v[46:47], v[98:99], v[184:185]
	v_pk_fma_f32 v[48:49], v[48:49], v[100:101], v[186:187]
	s_mov_b64 s[14:15], 0x80000
	v_lshl_add_u64 v[174:175], v[152:153], 0, s[14:15]
	global_store_dwordx4 v[174:175], v[62:65], off
	global_store_dwordx4 v[174:175], v[58:61], off offset:16
	global_store_dwordx4 v[174:175], v[50:53], off offset:128
	global_store_dwordx4 v[174:175], v[46:49], off offset:144
	s_mov_b64 s[14:15], 0xa0000
	v_lshl_add_u64 v[172:173], v[154:155], 0, s[14:15]
	global_load_dwordx4 v[156:159], v[172:173], off
	global_load_dwordx4 v[176:179], v[172:173], off offset:16
	global_load_dwordx4 v[180:183], v[172:173], off offset:128
	global_load_dwordx4 v[184:187], v[172:173], off offset:144
	s_waitcnt vmcnt(8)
	v_pk_fma_f32 v[54:55], v[54:55], v[110:111], v[188:189]
	v_pk_fma_f32 v[56:57], v[56:57], v[112:113], v[190:191]
	v_pk_fma_f32 v[42:43], v[42:43], v[102:103], v[192:193]
	v_pk_fma_f32 v[44:45], v[44:45], v[104:105], v[194:195]
	v_pk_fma_f32 v[38:39], v[38:39], v[106:107], v[196:197]
	v_pk_fma_f32 v[40:41], v[40:41], v[108:109], v[198:199]
	v_pk_fma_f32 v[34:35], v[34:35], v[98:99], v[230:231]
	v_pk_fma_f32 v[36:37], v[36:37], v[100:101], v[232:233]
	s_mov_b64 s[14:15], 0x90000
	v_lshl_add_u64 v[174:175], v[152:153], 0, s[14:15]
	global_store_dwordx4 v[174:175], v[54:57], off
	global_store_dwordx4 v[174:175], v[42:45], off offset:16
	global_store_dwordx4 v[174:175], v[38:41], off offset:128
	global_store_dwordx4 v[174:175], v[34:37], off offset:144
	s_mov_b64 s[14:15], 0xb0000
	v_lshl_add_u64 v[172:173], v[154:155], 0, s[14:15]
	global_load_dwordx4 v[188:191], v[172:173], off
	global_load_dwordx4 v[192:195], v[172:173], off offset:16
	global_load_dwordx4 v[196:199], v[172:173], off offset:128
	global_load_dwordx4 v[230:233], v[172:173], off offset:144
	s_waitcnt vmcnt(8)
	v_pk_fma_f32 v[30:31], v[30:31], v[110:111], v[156:157]
	v_pk_fma_f32 v[32:33], v[32:33], v[112:113], v[158:159]
	v_pk_fma_f32 v[26:27], v[26:27], v[102:103], v[176:177]
	v_pk_fma_f32 v[28:29], v[28:29], v[104:105], v[178:179]
	v_pk_fma_f32 v[14:15], v[14:15], v[106:107], v[180:181]
	v_pk_fma_f32 v[16:17], v[16:17], v[108:109], v[182:183]
	v_pk_fma_f32 v[10:11], v[10:11], v[98:99], v[184:185]
	v_pk_fma_f32 v[12:13], v[12:13], v[100:101], v[186:187]
	s_mov_b64 s[14:15], 0xa0000
	v_lshl_add_u64 v[174:175], v[152:153], 0, s[14:15]
	global_store_dwordx4 v[174:175], v[30:33], off
	global_store_dwordx4 v[174:175], v[26:29], off offset:16
	global_store_dwordx4 v[174:175], v[14:17], off offset:128
	global_store_dwordx4 v[174:175], v[10:13], off offset:144
	s_waitcnt vmcnt(4)
	v_pk_fma_f32 v[22:23], v[22:23], v[110:111], v[188:189]
	v_pk_fma_f32 v[24:25], v[24:25], v[112:113], v[190:191]
	v_pk_fma_f32 v[18:19], v[18:19], v[102:103], v[192:193]
	v_pk_fma_f32 v[20:21], v[20:21], v[104:105], v[194:195]
	v_pk_fma_f32 v[6:7], v[6:7], v[106:107], v[196:197]
	v_pk_fma_f32 v[8:9], v[8:9], v[108:109], v[198:199]
	v_pk_fma_f32 v[2:3], v[2:3], v[98:99], v[230:231]
	v_pk_fma_f32 v[4:5], v[4:5], v[100:101], v[232:233]
	s_mov_b64 s[14:15], 0xb0000
	v_lshl_add_u64 v[174:175], v[152:153], 0, s[14:15]
	global_store_dwordx4 v[174:175], v[22:25], off
	global_store_dwordx4 v[174:175], v[18:21], off offset:16
	global_store_dwordx4 v[174:175], v[6:9], off offset:128
	global_store_dwordx4 v[174:175], v[2:5], off offset:144
	s_mov_b64 s[16:17], s[8:9]
	s_and_b64 vcc, exec, s[4:5]
	s_mov_b64 s[14:15], s[6:7]
	s_cbranch_vccnz .LBB0_1252
	s_branch .LBB0_1240
.Lfd_epi_h3:
	s_waitcnt vmcnt(4)
	v_pk_fma_f32 v[86:87], v[86:87], v[110:111], v[188:189]
	v_pk_fma_f32 v[88:89], v[88:89], v[112:113], v[190:191]
	v_pk_fma_f32 v[74:75], v[74:75], v[102:103], v[192:193]
	v_pk_fma_f32 v[76:77], v[76:77], v[104:105], v[194:195]
	v_pk_fma_f32 v[70:71], v[70:71], v[106:107], v[196:197]
	v_pk_fma_f32 v[72:73], v[72:73], v[108:109], v[198:199]
	v_pk_fma_f32 v[66:67], v[66:67], v[98:99], v[230:231]
	v_pk_fma_f32 v[68:69], v[68:69], v[100:101], v[232:233]
	s_mov_b64 s[14:15], 0x30000
	v_lshl_add_u64 v[174:175], v[152:153], 0, s[14:15]
	global_store_dwordx4 v[174:175], v[86:89], off
	global_store_dwordx4 v[174:175], v[74:77], off offset:16
	global_store_dwordx4 v[174:175], v[70:73], off offset:128
	global_store_dwordx4 v[174:175], v[66:69], off offset:144
	s_branch .Lfd_half_done
	s_branch .LBB0_1240
